# v23 + E3 short-conv job rewritten: all row/weight loads up front (4 dependent round trips -> 1), EpiResid prologue gate load kept in flight
# baseline (speedup 1.0000x reference)
.LBB0_678:
	s_ashr_i32 s0, s6, 31
	s_lshr_b32 s0, s0, 26
	s_add_i32 s0, s6, s0
	s_and_b32 s1, s0, 0xffffffc0
	s_sub_i32 s5, s6, s1
	s_mul_i32 s4, s5, 0xc0
	s_lshl_b32 s2, s0, 2
	v_mov_b32_e32 v100, v155
	s_add_i32 s0, s4, 0xbf
	v_mov_b32_e32 v0, s0
	v_mov_b32_e32 v1, s4
	v_cmp_gt_i32_e32 vcc, s31, v100
	s_movk_i32 s0, 0x1800
	s_nop 0
	v_cndmask_b32_e32 v1, v0, v1, vcc
	v_add_u32_e32 v0, 0xfffff000, v1
	v_lshrrev_b32_e32 v2, 10, v0
	v_mad_u32_u24 v2, v2, s0, s0
	s_movk_i32 s0, 0xfff
	v_mov_b32_e32 v0, s2
	v_cmp_lt_i32_e32 vcc, s0, v1
	v_bfi_b32 v0, s39, v100, v0
	v_ashrrev_i32_e32 v1, 31, v0
	v_cndmask_b32_e32 v128, 0, v2, vcc
	v_lshl_add_u64 v[2:3], v[128:129], 2, s[54:55]
	v_lshl_add_u64 v[2:3], v[0:1], 2, v[2:3]
	s_barrier
	v_lshrrev_b32_e32 v244, 4, v100
	v_xor_b32_e32 v244, v244, v100
	v_and_b32_e32 v244, 7, v244
	v_lshlrev_b32_e32 v244, 4, v244
	v_mov_b32_e32 v245, 0
	v_lshrrev_b32_e32 v243, 3, v100
	v_lshlrev_b32_e32 v246, 4, v100
	s_nop 0
	v_readfirstlane_b32 s3, v246
	v_add_u32_e32 v246, s4, v243
	v_mov_b32_e32 v247, 0
	v_lshlrev_b64 v[246:247], 11, v[246:247]
	v_lshl_add_u64 v[246:247], s[50:51], 0, v[246:247]
	v_lshl_add_u64 v[246:247], v[246:247], 0, v[244:245]
	s_and_b32 s0, s2, 0xffffff00
	v_add_u32_e32 v243, s0, v243
	s_mov_b64 s[0:1], 0x20000
	s_mov_b32 m0, s3
	s_nop 0
	global_load_lds_dwordx4 v[246:247], off
	s_add_i32 m0, s3, 0x2000
	v_lshl_add_u64 v[246:247], v[246:247], 0, s[0:1]
	global_load_lds_dwordx4 v[246:247], off
	s_add_i32 m0, s3, 0x4000
	v_lshl_add_u64 v[246:247], v[246:247], 0, s[0:1]
	global_load_lds_dwordx4 v[246:247], off
	v_mov_b32_e32 v246, v243
	v_mov_b32_e32 v247, 0
	v_lshlrev_b64 v[246:247], 11, v[246:247]
	v_lshl_add_u64 v[246:247], s[60:61], 0, v[246:247]
	v_lshl_add_u64 v[246:247], v[246:247], 0, v[244:245]
	s_add_i32 m0, s3, 0x6000
	s_nop 0
	global_load_lds_dwordx4 v[246:247], off
	s_add_i32 m0, s3, 0x8000
	v_lshl_add_u64 v[246:247], v[246:247], 0, s[0:1]
	global_load_lds_dwordx4 v[246:247], off
	s_add_i32 m0, s3, 0xa000
	v_lshl_add_u64 v[246:247], v[246:247], 0, s[0:1]
	global_load_lds_dwordx4 v[246:247], off
	s_add_i32 m0, s3, 0xc000
	v_lshl_add_u64 v[246:247], v[246:247], 0, s[0:1]
	global_load_lds_dwordx4 v[246:247], off
	global_load_dword v246, v[2:3], off
	v_readlane_b32 s8, v241, 20
	v_readlane_b32 s9, v241, 21
	v_mov_b32_e32 v32, 0
	s_andn2_b64 vcc, exec, s[8:9]
	v_cndmask_b32_e64 v2, 0, 1, s[8:9]
	v_cmp_ne_u32_e64 s[0:1], 1, v2
	v_lshl_add_u32 v2, v100, 2, v167
	v_mov_b32_e32 v3, 0
	s_cbranch_vccnz .LBB0_680
	v_lshl_add_u64 v[4:5], v[128:129], 2, s[58:59]
	v_lshlrev_b64 v[0:1], 2, v[0:1]
	v_lshl_add_u64 v[4:5], v[4:5], 0, v[0:1]
	v_lshl_add_u64 v[0:1], s[56:57], 0, v[0:1]
	global_load_dword v3, v[4:5], off
	s_nop 0
	global_load_dword v0, v[0:1], off
	s_waitcnt vmcnt(1)
	v_add_f32_e32 v1, 1.0, v3
	s_waitcnt vmcnt(0)
	v_mul_f32_e32 v3, v0, v1
.LBB0_680:
	s_waitcnt vmcnt(0)
	ds_write_b32 v2, v246
	v_ashrrev_i32_e32 v103, 6, v100
	v_lshrrev_b32_e32 v0, 30, v103
	v_add_u32_e32 v0, v103, v0
	v_ashrrev_i32_e32 v10, 2, v0
	v_mul_i32_i24_e32 v0, 4, v10
	v_ashrrev_i32_e32 v6, 3, v100
	v_sub_u32_e32 v11, v103, v0
	v_lshrrev_b32_e32 v13, 4, v100
	v_add_u32_e32 v0, s4, v6
	v_xor_b32_e32 v7, v13, v100
	v_ashrrev_i32_e32 v1, 31, v0
	v_lshlrev_b64 v[0:1], 11, v[0:1]
	v_lshlrev_b32_e32 v7, 4, v7
	v_lshlrev_b32_e32 v109, 4, v100
	s_and_b32 s8, s2, 0xffffff00
	v_lshl_add_u64 v[4:5], s[50:51], 0, v[0:1]
	v_and_b32_e32 v128, 0x70, v7
	v_readfirstlane_b32 s2, v109
	v_add_u32_e32 v14, 0x2000, v109
	v_lshl_add_u64 v[4:5], v[4:5], 0, v[128:129]
	s_mov_b32 m0, s2
	s_mov_b64 s[10:11], 0x20000
	v_readfirstlane_b32 s2, v14
	ds_write_b32 v2, v3 offset:2048
	v_lshl_add_u64 v[2:3], v[4:5], 0, s[10:11]
	s_mov_b32 m0, s2
	s_mov_b64 s[12:13], 0x40000
	v_lshl_add_u64 v[2:3], v[4:5], 0, s[12:13]
	v_add_u32_e32 v4, 0x4000, v109
	v_add_u32_e32 v6, s8, v6
	v_readfirstlane_b32 s2, v4
	v_ashrrev_i32_e32 v7, 31, v6
	s_mov_b32 m0, s2
	v_lshlrev_b64 v[6:7], 11, v[6:7]
	v_add_u32_e32 v2, 0x6000, v109
	v_lshl_add_u64 v[8:9], s[60:61], 0, v[6:7]
	v_readfirstlane_b32 s2, v2
	v_add_u32_e32 v4, 0x8000, v109
	v_lshl_add_u64 v[8:9], v[8:9], 0, v[128:129]
	s_mov_b32 m0, s2
	v_readfirstlane_b32 s2, v4
	v_add_u32_e32 v4, 0xa000, v109
	v_lshl_add_u64 v[2:3], v[8:9], 0, s[10:11]
	s_mov_b32 m0, s2
	v_readfirstlane_b32 s2, v4
	v_lshl_add_u64 v[2:3], v[8:9], 0, s[12:13]
	s_mov_b32 m0, s2
	s_mov_b64 s[2:3], 0x60000
	v_add_u32_e32 v4, 0xc000, v109
	v_lshl_add_u64 v[2:3], v[8:9], 0, s[2:3]
	v_readfirstlane_b32 s2, v4
	s_mov_b32 m0, s2
	v_and_b32_e32 v102, 31, v100
	v_lshlrev_b32_e32 v105, 6, v11
	v_or_b32_e32 v3, v105, v102
	v_mul_i32_i24_e32 v106, 0x60, v10
	v_bfe_u32 v12, v100, 5, 1
	v_lshrrev_b32_e32 v104, 1, v100
	v_lshlrev_b32_e32 v112, 7, v3
	v_or_b32_e32 v3, v106, v102
	v_bfe_u32 v2, v100, 1, 3
	v_lshlrev_b32_e32 v113, 7, v3
	v_bitop3_b32 v3, v12, v104, 7 bitop3:0x78
	v_lshlrev_b32_e32 v111, 4, v3
	v_bitop3_b32 v3, v12, v2, 2 bitop3:0x36
	v_lshlrev_b32_e32 v110, 4, v3
	v_bitop3_b32 v3, v12, v2, 4 bitop3:0x36
	v_bitop3_b32 v2, v12, v2, 6 bitop3:0x36
	v_lshlrev_b32_e32 v107, 4, v2
	v_bitop3_b32 v2, v13, 7, v100 bitop3:0x48
	v_lshlrev_b32_e32 v2, 4, v2
	v_or_b32_e32 v6, v6, v2
	v_or_b32_e32 v0, v0, v2
	v_and_b32_e32 v101, 63, v100
	v_lshlrev_b32_e32 v108, 4, v3
	v_add_u32_e32 v114, 0x6000, v112
	v_lshl_add_u64 v[96:97], s[62:63], 0, v[6:7]
	v_lshl_add_u64 v[98:99], s[14:15], 0, v[0:1]
	s_mov_b32 s7, 0
	s_mov_b64 s[2:3], 0
	v_mov_b32_e32 v33, v32
	v_mov_b32_e32 v34, v32
	v_mov_b32_e32 v35, v32
	v_mov_b32_e32 v36, v32
	v_mov_b32_e32 v37, v32
	v_mov_b32_e32 v38, v32
	v_mov_b32_e32 v39, v32
	v_mov_b32_e32 v40, v32
	v_mov_b32_e32 v41, v32
	v_mov_b32_e32 v42, v32
	v_mov_b32_e32 v43, v32
	v_mov_b32_e32 v44, v32
	v_mov_b32_e32 v45, v32
	v_mov_b32_e32 v46, v32
	v_mov_b32_e32 v47, v32
	v_mov_b32_e32 v64, v32
	v_mov_b32_e32 v65, v32
	v_mov_b32_e32 v66, v32
	v_mov_b32_e32 v67, v32
	v_mov_b32_e32 v68, v32
	v_mov_b32_e32 v69, v32
	v_mov_b32_e32 v70, v32
	v_mov_b32_e32 v71, v32
	v_mov_b32_e32 v72, v32
	v_mov_b32_e32 v73, v32
	v_mov_b32_e32 v74, v32
	v_mov_b32_e32 v75, v32
	v_mov_b32_e32 v76, v32
	v_mov_b32_e32 v77, v32
	v_mov_b32_e32 v78, v32
	v_mov_b32_e32 v79, v32
	v_mov_b32_e32 v0, v32
	v_mov_b32_e32 v1, v32
	v_mov_b32_e32 v2, v32
	v_mov_b32_e32 v3, v32
	v_mov_b32_e32 v4, v32
	v_mov_b32_e32 v5, v32
	v_mov_b32_e32 v6, v32
	v_mov_b32_e32 v7, v32
	v_mov_b32_e32 v8, v32
	v_mov_b32_e32 v9, v32
	v_mov_b32_e32 v10, v32
	v_mov_b32_e32 v11, v32
	v_mov_b32_e32 v12, v32
	v_mov_b32_e32 v13, v32
	v_mov_b32_e32 v14, v32
	v_mov_b32_e32 v15, v32
	v_mov_b32_e32 v80, v32
	v_mov_b32_e32 v81, v32
	v_mov_b32_e32 v82, v32
	v_mov_b32_e32 v83, v32
	v_mov_b32_e32 v84, v32
	v_mov_b32_e32 v85, v32
	v_mov_b32_e32 v86, v32
	v_mov_b32_e32 v87, v32
	v_mov_b32_e32 v88, v32
	v_mov_b32_e32 v89, v32
	v_mov_b32_e32 v90, v32
	v_mov_b32_e32 v91, v32
	v_mov_b32_e32 v92, v32
	v_mov_b32_e32 v93, v32
	v_mov_b32_e32 v94, v32
	v_mov_b32_e32 v95, v32
	v_mov_b32_e32 v48, v32
	v_mov_b32_e32 v49, v32
	v_mov_b32_e32 v50, v32
	v_mov_b32_e32 v51, v32
	v_mov_b32_e32 v52, v32
	v_mov_b32_e32 v53, v32
	v_mov_b32_e32 v54, v32
	v_mov_b32_e32 v55, v32
	v_mov_b32_e32 v56, v32
	v_mov_b32_e32 v57, v32
	v_mov_b32_e32 v58, v32
	v_mov_b32_e32 v59, v32
	v_mov_b32_e32 v60, v32
	v_mov_b32_e32 v61, v32
	v_mov_b32_e32 v62, v32
	v_mov_b32_e32 v63, v32
	v_mov_b32_e32 v16, v32
	v_mov_b32_e32 v17, v32
	v_mov_b32_e32 v18, v32
	v_mov_b32_e32 v19, v32
	v_mov_b32_e32 v20, v32
	v_mov_b32_e32 v21, v32
	v_mov_b32_e32 v22, v32
	v_mov_b32_e32 v23, v32
	v_mov_b32_e32 v24, v32
	v_mov_b32_e32 v25, v32
	v_mov_b32_e32 v26, v32
	v_mov_b32_e32 v27, v32
	v_mov_b32_e32 v28, v32
	v_mov_b32_e32 v29, v32
	v_mov_b32_e32 v30, v32
	v_mov_b32_e32 v31, v32
	s_mov_b64 s[12:13], 0x8794080
	s_mov_b64 s[16:17], 0x87b4080
	s_mov_b64 s[18:19], 0x87d4080

.LBB0_1054:
	v_mov_b32_e32 v1, v155
	s_movk_i32 s2, 0x1000
	v_lshl_add_u32 v0, v0, 9, v1
	v_ashrrev_i32_e32 v130, 6, v0
	v_lshlrev_b32_e32 v0, 3, v1
	v_cmp_gt_i32_e32 vcc, s2, v130
	v_and_b32_e32 v0, 0x1f8, v0
	v_readlane_b32 s4, v241, 6
	v_cndmask_b32_e32 v1, v169, v170, vcc
	v_readlane_b32 s5, v241, 7
	v_cndmask_b32_e32 v17, v171, v172, vcc
	v_and_b32_e32 v16, v1, v130
	v_lshlrev_b32_e32 v128, 2, v0
	v_lshlrev_b32_e32 v131, 1, v0
	v_mul_u32_u24_e32 v243, 0xc00, v130
	v_add_u32_e32 v243, v243, v131
	v_add_u32_e32 v18, -1, v16
	v_add_u32_e32 v19, 1, v16
	v_cmp_lt_u32_e32 vcc, v18, v17
	s_nop 1
	s_and_b64 s[2:3], vcc, exec
	s_cbranch_scc0 .Lconv_a0
	global_load_dwordx4 v[0:3], v243, s[4:5] offset:-2048
	global_load_dwordx4 v[4:7], v243, s[4:5] offset:-1024
	s_branch .Lconv_a1
.Lconv_a0:
	v_mov_b32_e32 v0, 0
	v_mov_b32_e32 v1, 0
	v_mov_b32_e32 v2, 0
	v_mov_b32_e32 v3, 0
	v_mov_b32_e32 v4, 0
	v_mov_b32_e32 v5, 0
	v_mov_b32_e32 v6, 0
	v_mov_b32_e32 v7, 0
.Lconv_a1:
	v_cmp_lt_u32_e32 vcc, v19, v17
	v_add_u32_e32 v24, 0xc00, v243
	s_nop 1
	s_and_b64 s[2:3], vcc, exec
	s_cbranch_scc0 .Lconv_c0
	global_load_dwordx4 v[16:19], v24, s[4:5] offset:1024
	global_load_dwordx4 v[20:23], v24, s[4:5] offset:2048
	s_branch .Lconv_c1
.Lconv_c0:
	v_mov_b32_e32 v16, 0
	v_mov_b32_e32 v17, 0
	v_mov_b32_e32 v18, 0
	v_mov_b32_e32 v19, 0
	v_mov_b32_e32 v20, 0
	v_mov_b32_e32 v21, 0
	v_mov_b32_e32 v22, 0
	v_mov_b32_e32 v23, 0
.Lconv_c1:
	global_load_dwordx4 v[8:11], v243, s[4:5] offset:1024
	global_load_dwordx4 v[12:15], v243, s[4:5] offset:2048
	global_load_dwordx4 v[24:27], v243, s[4:5]
	v_readlane_b32 s2, v241, 48
	v_readlane_b32 s3, v241, 49
	v_lshl_add_u32 v243, v130, 11, v131
	s_nop 4
	global_load_dwordx4 v[28:31], v128, s[2:3]
	global_load_dwordx4 v[32:35], v128, s[2:3] offset:16
	global_load_dwordx4 v[36:39], v128, s[2:3] offset:2048
	global_load_dwordx4 v[132:135], v128, s[2:3] offset:2064
	s_add_u32 s2, s2, 0x1000
	s_addc_u32 s3, s3, 0
	v_readlane_b32 s4, v241, 8
	v_readlane_b32 s5, v241, 9
	s_waitcnt vmcnt(2)
	v_lshlrev_b32_e32 v244, 16, v0
	v_and_b32_e32 v0, 0xffff0000, v0
	v_lshlrev_b32_e32 v245, 16, v4
	v_and_b32_e32 v4, 0xffff0000, v4
	v_mul_f32_e32 v244, v244, v245
	v_mul_f32_e32 v0, v0, v4
	v_mul_f32_e32 v4, v28, v244
	v_mul_f32_e32 v0, v29, v0
	v_lshlrev_b32_e32 v244, 16, v1
	v_and_b32_e32 v1, 0xffff0000, v1
	v_lshlrev_b32_e32 v245, 16, v5
	v_and_b32_e32 v5, 0xffff0000, v5
	v_mul_f32_e32 v244, v244, v245
	v_mul_f32_e32 v1, v1, v5
	v_mul_f32_e32 v5, v30, v244
	v_mul_f32_e32 v1, v31, v1
	v_lshlrev_b32_e32 v244, 16, v2
	v_and_b32_e32 v2, 0xffff0000, v2
	v_lshlrev_b32_e32 v245, 16, v6
	v_and_b32_e32 v6, 0xffff0000, v6
	v_mul_f32_e32 v244, v244, v245
	v_mul_f32_e32 v2, v2, v6
	v_mul_f32_e32 v6, v32, v244
	v_mul_f32_e32 v2, v33, v2
	v_lshlrev_b32_e32 v244, 16, v3
	v_and_b32_e32 v3, 0xffff0000, v3
	v_lshlrev_b32_e32 v245, 16, v7
	v_and_b32_e32 v7, 0xffff0000, v7
	v_mul_f32_e32 v244, v244, v245
	v_mul_f32_e32 v3, v3, v7
	v_mul_f32_e32 v7, v34, v244
	v_mul_f32_e32 v3, v35, v3
	global_load_dwordx4 v[28:31], v128, s[2:3]
	global_load_dwordx4 v[32:35], v128, s[2:3] offset:16
	s_waitcnt vmcnt(2)
	v_lshlrev_b32_e32 v244, 16, v8
	v_and_b32_e32 v8, 0xffff0000, v8
	v_lshlrev_b32_e32 v245, 16, v12
	v_and_b32_e32 v12, 0xffff0000, v12
	v_mul_f32_e32 v244, v244, v245
	v_mul_f32_e32 v8, v8, v12
	v_fmac_f32_e32 v4, v36, v244
	v_fmac_f32_e32 v0, v37, v8
	v_lshlrev_b32_e32 v244, 16, v9
	v_and_b32_e32 v9, 0xffff0000, v9
	v_lshlrev_b32_e32 v245, 16, v13
	v_and_b32_e32 v13, 0xffff0000, v13
	v_mul_f32_e32 v244, v244, v245
	v_mul_f32_e32 v9, v9, v13
	v_fmac_f32_e32 v5, v38, v244
	v_fmac_f32_e32 v1, v39, v9
	v_lshlrev_b32_e32 v244, 16, v10
	v_and_b32_e32 v10, 0xffff0000, v10
	v_lshlrev_b32_e32 v245, 16, v14
	v_and_b32_e32 v14, 0xffff0000, v14
	v_mul_f32_e32 v244, v244, v245
	v_mul_f32_e32 v10, v10, v14
	v_fmac_f32_e32 v6, v132, v244
	v_fmac_f32_e32 v2, v133, v10
	v_lshlrev_b32_e32 v244, 16, v11
	v_and_b32_e32 v11, 0xffff0000, v11
	v_lshlrev_b32_e32 v245, 16, v15
	v_and_b32_e32 v15, 0xffff0000, v15
	v_mul_f32_e32 v244, v244, v245
	v_mul_f32_e32 v11, v11, v15
	v_fmac_f32_e32 v7, v134, v244
	v_fmac_f32_e32 v3, v135, v11
	s_waitcnt vmcnt(0)
	v_lshlrev_b32_e32 v244, 16, v16
	v_and_b32_e32 v16, 0xffff0000, v16
	v_lshlrev_b32_e32 v245, 16, v20
	v_and_b32_e32 v20, 0xffff0000, v20
	v_mul_f32_e32 v244, v244, v245
	v_mul_f32_e32 v16, v16, v20
	v_fmac_f32_e32 v4, v28, v244
	v_fmac_f32_e32 v0, v29, v16
	v_lshlrev_b32_e32 v244, 16, v17
	v_and_b32_e32 v17, 0xffff0000, v17
	v_lshlrev_b32_e32 v245, 16, v21
	v_and_b32_e32 v21, 0xffff0000, v21
	v_mul_f32_e32 v244, v244, v245
	v_mul_f32_e32 v17, v17, v21
	v_fmac_f32_e32 v5, v30, v244
	v_fmac_f32_e32 v1, v31, v17
	v_lshlrev_b32_e32 v244, 16, v18
	v_and_b32_e32 v18, 0xffff0000, v18
	v_lshlrev_b32_e32 v245, 16, v22
	v_and_b32_e32 v22, 0xffff0000, v22
	v_mul_f32_e32 v244, v244, v245
	v_mul_f32_e32 v18, v18, v22
	v_fmac_f32_e32 v6, v32, v244
	v_fmac_f32_e32 v2, v33, v18
	v_lshlrev_b32_e32 v244, 16, v19
	v_and_b32_e32 v19, 0xffff0000, v19
	v_lshlrev_b32_e32 v245, 16, v23
	v_and_b32_e32 v23, 0xffff0000, v23
	v_mul_f32_e32 v244, v244, v245
	v_mul_f32_e32 v19, v19, v23
	v_fmac_f32_e32 v7, v34, v244
	v_fmac_f32_e32 v3, v35, v19
	v_lshlrev_b32_e32 v244, 16, v24
	v_and_b32_e32 v245, 0xffff0000, v24
	v_mul_f32_e32 v4, v4, v244
	v_mul_f32_e32 v0, v0, v245
	v_cvt_pk_bf16_f32 v24, v4, v0
	v_lshlrev_b32_e32 v244, 16, v25
	v_and_b32_e32 v245, 0xffff0000, v25
	v_mul_f32_e32 v5, v5, v244
	v_mul_f32_e32 v1, v1, v245
	v_cvt_pk_bf16_f32 v25, v5, v1
	v_lshlrev_b32_e32 v244, 16, v26
	v_and_b32_e32 v245, 0xffff0000, v26
	v_mul_f32_e32 v6, v6, v244
	v_mul_f32_e32 v2, v2, v245
	v_cvt_pk_bf16_f32 v26, v6, v2
	v_lshlrev_b32_e32 v244, 16, v27
	v_and_b32_e32 v245, 0xffff0000, v27
	v_mul_f32_e32 v7, v7, v244
	v_mul_f32_e32 v3, v3, v245
	v_cvt_pk_bf16_f32 v27, v7, v3
	global_store_dwordx4 v243, v[24:27], s[4:5]
	v_mov_b32_e32 v128, 0
	v_mov_b32_e32 v130, 0
	v_mov_b32_e32 v131, 0
	v_mov_b32_e32 v132, 0
	v_mov_b32_e32 v133, 0
	v_mov_b32_e32 v134, 0
	v_mov_b32_e32 v135, 0
	s_and_b64 vcc, exec, s[0:1]
	s_cbranch_vccnz .LBB0_1036

.LBB0_1220:
	s_ashr_i32 s0, s6, 31
	s_lshr_b32 s0, s0, 26
	s_add_i32 s0, s6, s0
	s_and_b32 s1, s0, 0xffffffc0
	s_sub_i32 s5, s6, s1
	s_mul_i32 s4, s5, 0xc0
	s_lshl_b32 s2, s0, 2
	v_mov_b32_e32 v100, v155
	s_add_i32 s0, s4, 0xbf
	v_mov_b32_e32 v0, s0
	v_mov_b32_e32 v1, s4
	v_cmp_gt_i32_e32 vcc, s31, v100
	s_movk_i32 s0, 0x1800
	s_nop 0
	v_cndmask_b32_e32 v1, v0, v1, vcc
	v_add_u32_e32 v0, 0xfffff000, v1
	v_lshrrev_b32_e32 v2, 10, v0
	v_mad_u32_u24 v2, v2, s0, s0
	s_movk_i32 s0, 0xfff
	v_mov_b32_e32 v0, s2
	v_cmp_lt_i32_e32 vcc, s0, v1
	v_bfi_b32 v0, s39, v100, v0
	v_ashrrev_i32_e32 v1, 31, v0
	v_cndmask_b32_e32 v128, 0, v2, vcc
	v_lshl_add_u64 v[2:3], v[128:129], 2, s[50:51]
	v_lshl_add_u64 v[2:3], v[0:1], 2, v[2:3]
	s_barrier
	v_lshrrev_b32_e32 v244, 4, v100
	v_xor_b32_e32 v244, v244, v100
	v_and_b32_e32 v244, 7, v244
	v_lshlrev_b32_e32 v244, 4, v244
	v_mov_b32_e32 v245, 0
	v_lshrrev_b32_e32 v243, 3, v100
	v_lshlrev_b32_e32 v246, 4, v100
	s_nop 0
	v_readfirstlane_b32 s3, v246
	v_add_u32_e32 v246, s4, v243
	v_mov_b32_e32 v247, 0
	v_lshlrev_b64 v[246:247], 11, v[246:247]
	v_lshl_add_u64 v[246:247], s[46:47], 0, v[246:247]
	v_lshl_add_u64 v[246:247], v[246:247], 0, v[244:245]
	s_and_b32 s0, s2, 0xffffff00
	v_add_u32_e32 v243, s0, v243
	s_mov_b64 s[0:1], 0x20000
	s_mov_b32 m0, s3
	s_nop 0
	global_load_lds_dwordx4 v[246:247], off
	s_add_i32 m0, s3, 0x2000
	v_lshl_add_u64 v[246:247], v[246:247], 0, s[0:1]
	global_load_lds_dwordx4 v[246:247], off
	s_add_i32 m0, s3, 0x4000
	v_lshl_add_u64 v[246:247], v[246:247], 0, s[0:1]
	global_load_lds_dwordx4 v[246:247], off
	v_mov_b32_e32 v246, v243
	v_mov_b32_e32 v247, 0
	v_lshlrev_b64 v[246:247], 11, v[246:247]
	v_lshl_add_u64 v[246:247], s[56:57], 0, v[246:247]
	v_lshl_add_u64 v[246:247], v[246:247], 0, v[244:245]
	s_add_i32 m0, s3, 0x6000
	s_nop 0
	global_load_lds_dwordx4 v[246:247], off
	s_add_i32 m0, s3, 0x8000
	v_lshl_add_u64 v[246:247], v[246:247], 0, s[0:1]
	global_load_lds_dwordx4 v[246:247], off
	s_add_i32 m0, s3, 0xa000
	v_lshl_add_u64 v[246:247], v[246:247], 0, s[0:1]
	global_load_lds_dwordx4 v[246:247], off
	s_add_i32 m0, s3, 0xc000
	v_lshl_add_u64 v[246:247], v[246:247], 0, s[0:1]
	global_load_lds_dwordx4 v[246:247], off
	global_load_dword v246, v[2:3], off
	v_readlane_b32 s8, v241, 20
	v_readlane_b32 s9, v241, 21
	v_mov_b32_e32 v32, 0
	s_andn2_b64 vcc, exec, s[8:9]
	v_cndmask_b32_e64 v2, 0, 1, s[8:9]
	v_cmp_ne_u32_e64 s[0:1], 1, v2
	v_lshl_add_u32 v2, v100, 2, v167
	v_mov_b32_e32 v3, 0
	s_cbranch_vccnz .LBB0_1222
	v_lshl_add_u64 v[4:5], v[128:129], 2, s[54:55]
	v_lshlrev_b64 v[0:1], 2, v[0:1]
	v_lshl_add_u64 v[4:5], v[4:5], 0, v[0:1]
	v_lshl_add_u64 v[0:1], s[52:53], 0, v[0:1]
	global_load_dword v3, v[4:5], off
	s_nop 0
	global_load_dword v0, v[0:1], off
	s_waitcnt vmcnt(1)
	v_add_f32_e32 v1, 1.0, v3
	s_waitcnt vmcnt(0)
	v_mul_f32_e32 v3, v0, v1
.LBB0_1222:
	s_waitcnt vmcnt(0)
	ds_write_b32 v2, v246
	v_ashrrev_i32_e32 v103, 6, v100
	v_lshrrev_b32_e32 v0, 30, v103
	v_add_u32_e32 v0, v103, v0
	v_ashrrev_i32_e32 v10, 2, v0
	v_mul_i32_i24_e32 v0, 4, v10
	v_ashrrev_i32_e32 v6, 3, v100
	v_sub_u32_e32 v11, v103, v0
	v_lshrrev_b32_e32 v13, 4, v100
	v_add_u32_e32 v0, s4, v6
	v_xor_b32_e32 v7, v13, v100
	v_ashrrev_i32_e32 v1, 31, v0
	v_lshlrev_b64 v[0:1], 11, v[0:1]
	v_lshlrev_b32_e32 v7, 4, v7
	v_lshlrev_b32_e32 v109, 4, v100
	s_and_b32 s8, s2, 0xffffff00
	v_lshl_add_u64 v[4:5], s[46:47], 0, v[0:1]
	v_and_b32_e32 v128, 0x70, v7
	v_readfirstlane_b32 s2, v109
	v_add_u32_e32 v14, 0x2000, v109
	v_lshl_add_u64 v[4:5], v[4:5], 0, v[128:129]
	s_mov_b32 m0, s2
	s_mov_b64 s[10:11], 0x20000
	v_readfirstlane_b32 s2, v14
	ds_write_b32 v2, v3 offset:2048
	v_lshl_add_u64 v[2:3], v[4:5], 0, s[10:11]
	s_mov_b32 m0, s2
	s_mov_b64 s[12:13], 0x40000
	v_lshl_add_u64 v[2:3], v[4:5], 0, s[12:13]
	v_add_u32_e32 v4, 0x4000, v109
	v_add_u32_e32 v6, s8, v6
	v_readfirstlane_b32 s2, v4
	v_ashrrev_i32_e32 v7, 31, v6
	s_mov_b32 m0, s2
	v_lshlrev_b64 v[6:7], 11, v[6:7]
	v_add_u32_e32 v2, 0x6000, v109
	v_lshl_add_u64 v[8:9], s[56:57], 0, v[6:7]
	v_readfirstlane_b32 s2, v2
	v_add_u32_e32 v4, 0x8000, v109
	v_lshl_add_u64 v[8:9], v[8:9], 0, v[128:129]
	s_mov_b32 m0, s2
	v_readfirstlane_b32 s2, v4
	v_add_u32_e32 v4, 0xa000, v109
	v_lshl_add_u64 v[2:3], v[8:9], 0, s[10:11]
	s_mov_b32 m0, s2
	v_readfirstlane_b32 s2, v4
	v_lshl_add_u64 v[2:3], v[8:9], 0, s[12:13]
	s_mov_b32 m0, s2
	s_mov_b64 s[2:3], 0x60000
	v_add_u32_e32 v4, 0xc000, v109
	v_lshl_add_u64 v[2:3], v[8:9], 0, s[2:3]
	v_readfirstlane_b32 s2, v4
	s_mov_b32 m0, s2
	v_and_b32_e32 v102, 31, v100
	v_lshlrev_b32_e32 v105, 6, v11
	v_or_b32_e32 v3, v105, v102
	v_mul_i32_i24_e32 v106, 0x60, v10
	v_bfe_u32 v12, v100, 5, 1
	v_lshrrev_b32_e32 v104, 1, v100
	v_lshlrev_b32_e32 v112, 7, v3
	v_or_b32_e32 v3, v106, v102
	v_bfe_u32 v2, v100, 1, 3
	v_lshlrev_b32_e32 v113, 7, v3
	v_bitop3_b32 v3, v12, v104, 7 bitop3:0x78
	v_lshlrev_b32_e32 v111, 4, v3
	v_bitop3_b32 v3, v12, v2, 2 bitop3:0x36
	v_lshlrev_b32_e32 v110, 4, v3
	v_bitop3_b32 v3, v12, v2, 4 bitop3:0x36
	v_bitop3_b32 v2, v12, v2, 6 bitop3:0x36
	v_lshlrev_b32_e32 v107, 4, v2
	v_bitop3_b32 v2, v13, 7, v100 bitop3:0x48
	v_lshlrev_b32_e32 v2, 4, v2
	v_or_b32_e32 v6, v6, v2
	v_or_b32_e32 v0, v0, v2
	v_and_b32_e32 v101, 63, v100
	v_lshlrev_b32_e32 v108, 4, v3
	v_add_u32_e32 v114, 0x6000, v112
	v_lshl_add_u64 v[96:97], s[58:59], 0, v[6:7]
	v_lshl_add_u64 v[98:99], s[14:15], 0, v[0:1]
	s_mov_b32 s7, 0
	s_mov_b64 s[2:3], 0
	v_mov_b32_e32 v33, v32
	v_mov_b32_e32 v34, v32
	v_mov_b32_e32 v35, v32
	v_mov_b32_e32 v36, v32
	v_mov_b32_e32 v37, v32
	v_mov_b32_e32 v38, v32
	v_mov_b32_e32 v39, v32
	v_mov_b32_e32 v40, v32
	v_mov_b32_e32 v41, v32
	v_mov_b32_e32 v42, v32
	v_mov_b32_e32 v43, v32
	v_mov_b32_e32 v44, v32
	v_mov_b32_e32 v45, v32
	v_mov_b32_e32 v46, v32
	v_mov_b32_e32 v47, v32
	v_mov_b32_e32 v64, v32
	v_mov_b32_e32 v65, v32
	v_mov_b32_e32 v66, v32
	v_mov_b32_e32 v67, v32
	v_mov_b32_e32 v68, v32
	v_mov_b32_e32 v69, v32
	v_mov_b32_e32 v70, v32
	v_mov_b32_e32 v71, v32
	v_mov_b32_e32 v72, v32
	v_mov_b32_e32 v73, v32
	v_mov_b32_e32 v74, v32
	v_mov_b32_e32 v75, v32
	v_mov_b32_e32 v76, v32
	v_mov_b32_e32 v77, v32
	v_mov_b32_e32 v78, v32
	v_mov_b32_e32 v79, v32
	v_mov_b32_e32 v0, v32
	v_mov_b32_e32 v1, v32
	v_mov_b32_e32 v2, v32
	v_mov_b32_e32 v3, v32
	v_mov_b32_e32 v4, v32
	v_mov_b32_e32 v5, v32
	v_mov_b32_e32 v6, v32
	v_mov_b32_e32 v7, v32
	v_mov_b32_e32 v8, v32
	v_mov_b32_e32 v9, v32
	v_mov_b32_e32 v10, v32
	v_mov_b32_e32 v11, v32
	v_mov_b32_e32 v12, v32
	v_mov_b32_e32 v13, v32
	v_mov_b32_e32 v14, v32
	v_mov_b32_e32 v15, v32
	v_mov_b32_e32 v80, v32
	v_mov_b32_e32 v81, v32
	v_mov_b32_e32 v82, v32
	v_mov_b32_e32 v83, v32
	v_mov_b32_e32 v84, v32
	v_mov_b32_e32 v85, v32
	v_mov_b32_e32 v86, v32
	v_mov_b32_e32 v87, v32
	v_mov_b32_e32 v88, v32
	v_mov_b32_e32 v89, v32
	v_mov_b32_e32 v90, v32
	v_mov_b32_e32 v91, v32
	v_mov_b32_e32 v92, v32
	v_mov_b32_e32 v93, v32
	v_mov_b32_e32 v94, v32
	v_mov_b32_e32 v95, v32
	v_mov_b32_e32 v48, v32
	v_mov_b32_e32 v49, v32
	v_mov_b32_e32 v50, v32
	v_mov_b32_e32 v51, v32
	v_mov_b32_e32 v52, v32
	v_mov_b32_e32 v53, v32
	v_mov_b32_e32 v54, v32
	v_mov_b32_e32 v55, v32
	v_mov_b32_e32 v56, v32
	v_mov_b32_e32 v57, v32
	v_mov_b32_e32 v58, v32
	v_mov_b32_e32 v59, v32
	v_mov_b32_e32 v60, v32
	v_mov_b32_e32 v61, v32
	v_mov_b32_e32 v62, v32
	v_mov_b32_e32 v63, v32
	v_mov_b32_e32 v16, v32
	v_mov_b32_e32 v17, v32
	v_mov_b32_e32 v18, v32
	v_mov_b32_e32 v19, v32
	v_mov_b32_e32 v20, v32
	v_mov_b32_e32 v21, v32
	v_mov_b32_e32 v22, v32
	v_mov_b32_e32 v23, v32
	v_mov_b32_e32 v24, v32
	v_mov_b32_e32 v25, v32
	v_mov_b32_e32 v26, v32
	v_mov_b32_e32 v27, v32
	v_mov_b32_e32 v28, v32
	v_mov_b32_e32 v29, v32
	v_mov_b32_e32 v30, v32
	v_mov_b32_e32 v31, v32
	s_mov_b64 s[12:13], 0x8794080
	s_mov_b64 s[16:17], 0x87b4080
	s_mov_b64 s[18:19], 0x87d4080

.LBB0_1431:
	s_ashr_i32 s0, s6, 31
	s_lshr_b32 s0, s0, 26
	s_add_i32 s0, s6, s0
	s_and_b32 s1, s0, 0xffffffc0
	s_sub_i32 s5, s6, s1
	s_mul_i32 s4, s5, 0xc0
	s_lshl_b32 s2, s0, 2
	v_mov_b32_e32 v100, v155
	s_add_i32 s0, s4, 0xbf
	v_mov_b32_e32 v0, s0
	v_mov_b32_e32 v1, s4
	v_cmp_gt_i32_e32 vcc, s31, v100
	s_movk_i32 s0, 0x1800
	s_nop 0
	v_cndmask_b32_e32 v1, v0, v1, vcc
	v_add_u32_e32 v0, 0xfffff000, v1
	v_lshrrev_b32_e32 v2, 10, v0
	v_mad_u32_u24 v2, v2, s0, s0
	s_movk_i32 s0, 0xfff
	v_mov_b32_e32 v0, s2
	v_cmp_lt_i32_e32 vcc, s0, v1
	v_bfi_b32 v0, s39, v100, v0
	v_ashrrev_i32_e32 v1, 31, v0
	v_cndmask_b32_e32 v128, 0, v2, vcc
	v_lshl_add_u64 v[2:3], v[128:129], 2, s[56:57]
	v_lshl_add_u64 v[2:3], v[0:1], 2, v[2:3]
	s_barrier
	v_lshrrev_b32_e32 v244, 4, v100
	v_xor_b32_e32 v244, v244, v100
	v_and_b32_e32 v244, 7, v244
	v_lshlrev_b32_e32 v244, 4, v244
	v_mov_b32_e32 v245, 0
	v_lshrrev_b32_e32 v243, 3, v100
	v_lshlrev_b32_e32 v246, 4, v100
	s_nop 0
	v_readfirstlane_b32 s3, v246
	v_add_u32_e32 v246, s4, v243
	v_mov_b32_e32 v247, 0
	v_lshlrev_b64 v[246:247], 13, v[246:247]
	v_lshl_add_u64 v[246:247], s[52:53], 0, v[246:247]
	v_lshl_add_u64 v[246:247], v[246:247], 0, v[244:245]
	s_and_b32 s0, s2, 0xffffff00
	v_add_u32_e32 v243, s0, v243
	s_mov_b64 s[0:1], 0x80000
	s_mov_b32 m0, s3
	s_nop 0
	global_load_lds_dwordx4 v[246:247], off
	s_add_i32 m0, s3, 0x2000
	v_lshl_add_u64 v[246:247], v[246:247], 0, s[0:1]
	global_load_lds_dwordx4 v[246:247], off
	s_add_i32 m0, s3, 0x4000
	v_lshl_add_u64 v[246:247], v[246:247], 0, s[0:1]
	global_load_lds_dwordx4 v[246:247], off
	v_mov_b32_e32 v246, v243
	v_mov_b32_e32 v247, 0
	v_lshlrev_b64 v[246:247], 13, v[246:247]
	v_lshl_add_u64 v[246:247], s[48:49], 0, v[246:247]
	v_lshl_add_u64 v[246:247], v[246:247], 0, v[244:245]
	s_add_i32 m0, s3, 0x6000
	s_nop 0
	global_load_lds_dwordx4 v[246:247], off
	s_add_i32 m0, s3, 0x8000
	v_lshl_add_u64 v[246:247], v[246:247], 0, s[0:1]
	global_load_lds_dwordx4 v[246:247], off
	s_add_i32 m0, s3, 0xa000
	v_lshl_add_u64 v[246:247], v[246:247], 0, s[0:1]
	global_load_lds_dwordx4 v[246:247], off
	s_add_i32 m0, s3, 0xc000
	v_lshl_add_u64 v[246:247], v[246:247], 0, s[0:1]
	global_load_lds_dwordx4 v[246:247], off
	global_load_dword v246, v[2:3], off
	v_cndmask_b32_e64 v2, 0, 1, s[58:59]
	v_cmp_ne_u32_e64 s[0:1], 1, v2
	v_lshl_add_u32 v2, v100, 2, v167
	v_mov_b32_e32 v32, 0
	s_andn2_b64 vcc, exec, s[58:59]
	v_mov_b32_e32 v3, 0
	s_cbranch_vccnz .LBB0_1433
	v_lshl_add_u64 v[4:5], v[128:129], 2, s[46:47]
	v_lshlrev_b64 v[0:1], 2, v[0:1]
	v_lshl_add_u64 v[4:5], v[4:5], 0, v[0:1]
	v_lshl_add_u64 v[0:1], s[44:45], 0, v[0:1]
	global_load_dword v3, v[4:5], off
	s_nop 0
	global_load_dword v0, v[0:1], off
	s_waitcnt vmcnt(1)
	v_add_f32_e32 v1, 1.0, v3
	s_waitcnt vmcnt(0)
	v_mul_f32_e32 v3, v0, v1
.LBB0_1433:
	s_waitcnt vmcnt(0)
	ds_write_b32 v2, v246
	v_ashrrev_i32_e32 v103, 6, v100
	v_lshrrev_b32_e32 v0, 30, v103
	v_add_u32_e32 v0, v103, v0
	v_ashrrev_i32_e32 v10, 2, v0
	v_mul_i32_i24_e32 v0, 4, v10
	v_ashrrev_i32_e32 v6, 3, v100
	v_sub_u32_e32 v11, v103, v0
	v_lshrrev_b32_e32 v13, 4, v100
	v_add_u32_e32 v0, s4, v6
	v_xor_b32_e32 v7, v13, v100
	v_ashrrev_i32_e32 v1, 31, v0
	v_lshlrev_b64 v[0:1], 13, v[0:1]
	v_lshlrev_b32_e32 v7, 4, v7
	v_lshlrev_b32_e32 v109, 4, v100
	s_and_b32 s8, s2, 0xffffff00
	v_lshl_add_u64 v[4:5], s[52:53], 0, v[0:1]
	v_and_b32_e32 v128, 0x70, v7
	v_readfirstlane_b32 s2, v109
	v_add_u32_e32 v14, 0x2000, v109
	v_lshl_add_u64 v[4:5], v[4:5], 0, v[128:129]
	s_mov_b32 m0, s2
	v_readfirstlane_b32 s2, v14
	ds_write_b32 v2, v3 offset:2048
	v_lshl_add_u64 v[2:3], v[4:5], 0, s[16:17]
	s_mov_b32 m0, s2
	v_add_u32_e32 v6, s8, v6
	v_lshl_add_u64 v[2:3], v[4:5], 0, s[20:21]
	v_add_u32_e32 v4, 0x4000, v109
	v_ashrrev_i32_e32 v7, 31, v6
	v_readfirstlane_b32 s2, v4
	s_mov_b32 m0, s2
	v_lshlrev_b64 v[6:7], 13, v[6:7]
	v_add_u32_e32 v2, 0x6000, v109
	v_lshl_add_u64 v[8:9], s[48:49], 0, v[6:7]
	v_readfirstlane_b32 s2, v2
	v_add_u32_e32 v4, 0x8000, v109
	v_lshl_add_u64 v[8:9], v[8:9], 0, v[128:129]
	s_mov_b32 m0, s2
	v_readfirstlane_b32 s2, v4
	v_add_u32_e32 v4, 0xa000, v109
	v_lshl_add_u64 v[2:3], v[8:9], 0, s[16:17]
	s_mov_b32 m0, s2
	v_readfirstlane_b32 s2, v4
	v_lshl_add_u64 v[2:3], v[8:9], 0, s[20:21]
	s_mov_b32 m0, s2
	s_mov_b64 s[2:3], 0x180000
	v_add_u32_e32 v4, 0xc000, v109
	v_lshl_add_u64 v[2:3], v[8:9], 0, s[2:3]
	v_readfirstlane_b32 s2, v4
	s_mov_b32 m0, s2
	v_and_b32_e32 v102, 31, v100
	v_lshlrev_b32_e32 v105, 6, v11
	v_or_b32_e32 v3, v105, v102
	v_mul_i32_i24_e32 v106, 0x60, v10
	v_bfe_u32 v12, v100, 5, 1
	v_lshrrev_b32_e32 v104, 1, v100
	v_lshlrev_b32_e32 v112, 7, v3
	v_or_b32_e32 v3, v106, v102
	v_bfe_u32 v2, v100, 1, 3
	v_lshlrev_b32_e32 v113, 7, v3
	v_bitop3_b32 v3, v12, v104, 7 bitop3:0x78
	v_lshlrev_b32_e32 v111, 4, v3
	v_bitop3_b32 v3, v12, v2, 2 bitop3:0x36
	v_lshlrev_b32_e32 v110, 4, v3
	v_bitop3_b32 v3, v12, v2, 4 bitop3:0x36
	v_bitop3_b32 v2, v12, v2, 6 bitop3:0x36
	v_lshlrev_b32_e32 v107, 4, v2
	v_bitop3_b32 v2, v13, 7, v100 bitop3:0x48
	v_lshlrev_b32_e32 v2, 4, v2
	v_or_b32_e32 v6, v6, v2
	v_or_b32_e32 v0, v0, v2
	v_and_b32_e32 v101, 63, v100
	v_lshlrev_b32_e32 v108, 4, v3
	v_add_u32_e32 v114, 0x6000, v112
	v_lshl_add_u64 v[96:97], s[60:61], 0, v[6:7]
	v_lshl_add_u64 v[98:99], s[14:15], 0, v[0:1]
	s_mov_b32 s7, 0
	s_mov_b64 s[2:3], 0
	v_mov_b32_e32 v33, v32
	v_mov_b32_e32 v34, v32
	v_mov_b32_e32 v35, v32
	v_mov_b32_e32 v36, v32
	v_mov_b32_e32 v37, v32
	v_mov_b32_e32 v38, v32
	v_mov_b32_e32 v39, v32
	v_mov_b32_e32 v40, v32
	v_mov_b32_e32 v41, v32
	v_mov_b32_e32 v42, v32
	v_mov_b32_e32 v43, v32
	v_mov_b32_e32 v44, v32
	v_mov_b32_e32 v45, v32
	v_mov_b32_e32 v46, v32
	v_mov_b32_e32 v47, v32
	v_mov_b32_e32 v64, v32
	v_mov_b32_e32 v65, v32
	v_mov_b32_e32 v66, v32
	v_mov_b32_e32 v67, v32
	v_mov_b32_e32 v68, v32
	v_mov_b32_e32 v69, v32
	v_mov_b32_e32 v70, v32
	v_mov_b32_e32 v71, v32
	v_mov_b32_e32 v72, v32
	v_mov_b32_e32 v73, v32
	v_mov_b32_e32 v74, v32
	v_mov_b32_e32 v75, v32
	v_mov_b32_e32 v76, v32
	v_mov_b32_e32 v77, v32
	v_mov_b32_e32 v78, v32
	v_mov_b32_e32 v79, v32
	v_mov_b32_e32 v0, v32
	v_mov_b32_e32 v1, v32
	v_mov_b32_e32 v2, v32
	v_mov_b32_e32 v3, v32
	v_mov_b32_e32 v4, v32
	v_mov_b32_e32 v5, v32
	v_mov_b32_e32 v6, v32
	v_mov_b32_e32 v7, v32
	v_mov_b32_e32 v8, v32
	v_mov_b32_e32 v9, v32
	v_mov_b32_e32 v10, v32
	v_mov_b32_e32 v11, v32
	v_mov_b32_e32 v12, v32
	v_mov_b32_e32 v13, v32
	v_mov_b32_e32 v14, v32
	v_mov_b32_e32 v15, v32
	v_mov_b32_e32 v80, v32
	v_mov_b32_e32 v81, v32
	v_mov_b32_e32 v82, v32
	v_mov_b32_e32 v83, v32
	v_mov_b32_e32 v84, v32
	v_mov_b32_e32 v85, v32
	v_mov_b32_e32 v86, v32
	v_mov_b32_e32 v87, v32
	v_mov_b32_e32 v88, v32
	v_mov_b32_e32 v89, v32
	v_mov_b32_e32 v90, v32
	v_mov_b32_e32 v91, v32
	v_mov_b32_e32 v92, v32
	v_mov_b32_e32 v93, v32
	v_mov_b32_e32 v94, v32
	v_mov_b32_e32 v95, v32
	v_mov_b32_e32 v48, v32
	v_mov_b32_e32 v49, v32
	v_mov_b32_e32 v50, v32
	v_mov_b32_e32 v51, v32
	v_mov_b32_e32 v52, v32
	v_mov_b32_e32 v53, v32
	v_mov_b32_e32 v54, v32
	v_mov_b32_e32 v55, v32
	v_mov_b32_e32 v56, v32
	v_mov_b32_e32 v57, v32
	v_mov_b32_e32 v58, v32
	v_mov_b32_e32 v59, v32
	v_mov_b32_e32 v60, v32
	v_mov_b32_e32 v61, v32
	v_mov_b32_e32 v62, v32
	v_mov_b32_e32 v63, v32
	v_mov_b32_e32 v16, v32
	v_mov_b32_e32 v17, v32
	v_mov_b32_e32 v18, v32
	v_mov_b32_e32 v19, v32
	v_mov_b32_e32 v20, v32
	v_mov_b32_e32 v21, v32
	v_mov_b32_e32 v22, v32
	v_mov_b32_e32 v23, v32
	v_mov_b32_e32 v24, v32
	v_mov_b32_e32 v25, v32
	v_mov_b32_e32 v26, v32
	v_mov_b32_e32 v27, v32
	v_mov_b32_e32 v28, v32
	v_mov_b32_e32 v29, v32
	v_mov_b32_e32 v30, v32
	v_mov_b32_e32 v31, v32
